# attention loops: stop-flag block address computed before the step rendezvous (SB: 6 instrs, DF late: 4 instrs off the post-barrier path); on top of loop-head shortcuts
# baseline (speedup 1.0000x reference)
.LBB0_356:
	s_and_b32 s90, s86, 8
	s_xor_b32 s91, s90, 8
	s_lshl_b32 s91, s91, 2
	s_add_i32 s91, s91, 0x241c0
	v_mov_b32_e32 v82, s91
	s_add_i32 s80, s0, s88
	s_add_i32 s84, s80, -2
	s_cmp_lt_i32 s84, 2
	s_mov_b64 s[82:83], -1
	s_cbranch_scc0 .Lsb_b8
	s_cmp_lg_u32 s80, 3
	s_cbranch_scc0 .LBB0_359
	s_waitcnt vmcnt(0) lgkmcnt(0)
	s_barrier
	s_mov_b64 s[82:83], 0

.LBB0_364:
	ds_read_b128 v[136:139], v82
	ds_read_b128 v[140:143], v82 offset:16
	s_waitcnt lgkmcnt(0)
	v_bitop3_b32 v136, v136, v137, v138 bitop3:0x80
	v_bitop3_b32 v140, v140, v141, v142 bitop3:0x80
	v_bitop3_b32 v136, v136, v139, v143 bitop3:0x80
	v_and_b32_e32 v82, v136, v140
	v_cmp_ne_u32_e64 s[82:83], 0, v82
	s_and_b64 vcc, exec, s[82:83]
	s_cbranch_vccnz .LBB0_355
	s_cmp_lt_i32 s84, 3
	s_cbranch_scc0 .LBB0_373
	s_andn2_b64 vcc, exec, s[72:73]
	s_cbranch_vccz .LBB0_374

.LBB0_393:
	s_and_b32 s28, s26, 8
	s_add_i32 s28, s28, 0x241c0
	v_mov_b32_e32 v0, s28
	s_mov_b64 s[8:9], -1
	s_cmp_eq_u32 s80, -4
	s_cbranch_scc1 .Llate_x392
	s_add_i32 s12, s80, 3
	s_cmp_lt_i32 s12, 2
	s_cbranch_scc0 .Llate_b8
	s_cmp_lg_u32 s80, -2
	s_cbranch_scc0 .LBB0_397
	s_waitcnt vmcnt(0) lgkmcnt(0)
	s_barrier
	s_mov_b64 s[8:9], 0

.LBB0_402:
	ds_read_b64 v[14:15], v0
	s_cmp_lt_i32 s12, 3
	s_cbranch_scc1 .LBB0_404
	s_and_b32 s13, s27, 0xc000
	s_cmp_gt_i32 s24, 1
	s_cselect_b32 s8, -2, 3
	s_add_i32 s8, s8, s24
	s_lshl_b32 s14, s8, 14
	s_lshl_b64 s[8:9], s[80:81], 14
	v_lshl_add_u64 v[80:81], v[180:181], 0, s[8:9]
	s_add_i32 s13, s76, s13
	s_mov_b32 s15, m0
	s_mov_b32 m0, s13
	s_nop 0
	global_load_lds_dwordx4 v[80:81], off
	s_mov_b32 m0, s15
	v_lshl_add_u64 v[80:81], v[80:81], 0, s[88:89]
	s_addk_i32 s13, 0x2000
	s_mov_b32 s15, m0
	s_mov_b32 m0, s13
	s_nop 0
	global_load_lds_dwordx4 v[80:81], off
	s_mov_b32 m0, s15
	v_lshl_add_u64 v[80:81], v[182:183], 0, s[8:9]
	s_add_i32 s8, s31, s14
	s_mov_b32 s9, m0
	s_mov_b32 m0, s8
	s_nop 0
	global_load_lds_dwordx4 v[80:81], off
	s_mov_b32 m0, s9
	v_lshl_add_u64 v[80:81], v[80:81], 0, s[88:89]
	s_addk_i32 s8, 0x2000
	s_mov_b32 s9, m0
	s_mov_b32 m0, s8
	s_nop 0
	global_load_lds_dwordx4 v[80:81], off
	s_mov_b32 m0, s9
